# v16 with sc1 (write-through) stores in the G1 epilogue
# speedup vs baseline: 1.0303x; 1.0017x over previous
; __device__ __forceinline__ bf16_t f2bf(float f) { return (bf16_t)(pack2(f, 0.f) & 0xffffu); }
; __device__ __forceinline__ float siluf_(float x) { return x * __builtin_amdgcn_rcpf(1.f + __expf(-x)); }
; template <int EPI>
; __device__ __forceinline__ void gemm_tile8p(const bf16_t* __restrict__ Ag, const bf16_t* __restrict__ Bg, int K, int nt, int brow, int bcol,
;                                             char* smem, void* outp, int ldo, int nvalid, int rowoff, int rowlim) {
;     ...
; #pragma unroll
;   for (int ai = 0; ai < 2; ++ai)
; #pragma unroll
;     for (int m = 0; m < 4; ++m)
; #pragma unroll
;       for (int j = 0; j < 4; ++j) {
;         const int rl = ai * HALF + wr * 64 + m * 16 + fq * 4 + j;
;         const size_t orow = (size_t)(rowoff + rl) * ldo;
;         if (EPI == EPI_GLU) {
; #pragma unroll
;           for (int n = 0; n < 2; ++n) {
;             const int col = (bcol >> 8) * 128 + wc * 32 + n * 16 + fr;
;             const float g = acc[ai][0][m][n][j], u = acc[ai][1][m][n][j];
;             if (rl < rowlim) ((bf16_t*)outp)[orow + col] = f2bf(siluf_(g) * u);
;           }
;         } else {
; #pragma unroll
;           for (int bj = 0; bj < 2; ++bj)
; #pragma unroll
;             for (int n = 0; n < 2; ++n) {
;               const int col = bcol + bj * HALF + wc * 32 + n * 16 + fr;
;               const float v = acc[ai][bj][m][n][j];
;               if (EPI == EPI_BF16) { if (rl < rowlim && col < nvalid) ((bf16_t*)outp)[orow + col] = f2bf(v); }
;               else { if (rl < rowlim) ((float*)outp)[orow + col] = v; }
;             }
;         }
;         __builtin_amdgcn_sched_barrier(0);
;       }
.LBB0_1069:
	s_or_b64 exec, exec, s[2:3]
	s_sub_i32 s4, 0x4080, s48
	v_or_b32_e32 v160, v136, v134
	v_lshlrev_b32_e32 v160, 9, v160
	v_and_b32_e32 v161, 1, v135
	v_lshl_or_b32 v160, v161, 3, v160
	v_lshrrev_b32_e32 v161, 1, v135
	v_lshl_or_b32 v162, v133, 2, v161
	v_xor_b32_e32 v162, v162, v134
	v_lshl_add_u32 v164, v162, 4, v160
	v_xor_b32_e32 v163, 2, v162
	v_lshl_add_u32 v165, v163, 4, v160
	v_add_u32_e32 v166, 0x100, v164
	v_add_u32_e32 v167, 0x100, v165
	v_add_u32_e32 v168, 0x10000, v164
	v_add_u32_e32 v169, 0x10000, v165
	v_add_u32_e32 v170, 0x10000, v166
	v_add_u32_e32 v171, 0x10000, v167
	v_cvt_pk_bf16_f32 v176, v124, v125
	v_cvt_pk_bf16_f32 v177, v126, v127
	v_cvt_pk_bf16_f32 v178, v116, v117
	v_cvt_pk_bf16_f32 v179, v118, v119
	v_cvt_pk_bf16_f32 v180, v120, v121
	v_cvt_pk_bf16_f32 v181, v122, v123
	v_cvt_pk_bf16_f32 v182, v112, v113
	v_cvt_pk_bf16_f32 v183, v114, v115
	ds_write_b64 v164, v[176:177]
	ds_write_b64 v165, v[178:179]
	ds_write_b64 v166, v[180:181]
	ds_write_b64 v167, v[182:183]
	v_cvt_pk_bf16_f32 v184, v108, v109
	v_cvt_pk_bf16_f32 v185, v110, v111
	v_cvt_pk_bf16_f32 v186, v100, v101
	v_cvt_pk_bf16_f32 v187, v102, v103
	v_cvt_pk_bf16_f32 v188, v104, v105
	v_cvt_pk_bf16_f32 v189, v106, v107
	v_cvt_pk_bf16_f32 v190, v96, v97
	v_cvt_pk_bf16_f32 v191, v98, v99
	ds_write_b64 v166, v[184:185] offset:8192
	ds_write_b64 v167, v[186:187] offset:8192
	ds_write_b64 v164, v[188:189] offset:8192
	ds_write_b64 v165, v[190:191] offset:8192
	v_cvt_pk_bf16_f32 v176, v92, v93
	v_cvt_pk_bf16_f32 v177, v94, v95
	v_cvt_pk_bf16_f32 v178, v84, v85
	v_cvt_pk_bf16_f32 v179, v86, v87
	v_cvt_pk_bf16_f32 v180, v88, v89
	v_cvt_pk_bf16_f32 v181, v90, v91
	v_cvt_pk_bf16_f32 v182, v80, v81
	v_cvt_pk_bf16_f32 v183, v82, v83
	ds_write_b64 v164, v[176:177] offset:16384
	ds_write_b64 v165, v[178:179] offset:16384
	ds_write_b64 v166, v[180:181] offset:16384
	ds_write_b64 v167, v[182:183] offset:16384
	v_cvt_pk_bf16_f32 v184, v76, v77
	v_cvt_pk_bf16_f32 v185, v78, v79
	v_cvt_pk_bf16_f32 v186, v68, v69
	v_cvt_pk_bf16_f32 v187, v70, v71
	v_cvt_pk_bf16_f32 v188, v72, v73
	v_cvt_pk_bf16_f32 v189, v74, v75
	v_cvt_pk_bf16_f32 v190, v64, v65
	v_cvt_pk_bf16_f32 v191, v66, v67
	ds_write_b64 v166, v[184:185] offset:24576
	ds_write_b64 v167, v[186:187] offset:24576
	ds_write_b64 v164, v[188:189] offset:24576
	ds_write_b64 v165, v[190:191] offset:24576
	v_cvt_pk_bf16_f32 v176, v60, v61
	v_cvt_pk_bf16_f32 v177, v62, v63
	v_cvt_pk_bf16_f32 v178, v52, v53
	v_cvt_pk_bf16_f32 v179, v54, v55
	v_cvt_pk_bf16_f32 v180, v56, v57
	v_cvt_pk_bf16_f32 v181, v58, v59
	v_cvt_pk_bf16_f32 v182, v48, v49
	v_cvt_pk_bf16_f32 v183, v50, v51
	ds_write_b64 v168, v[176:177]
	ds_write_b64 v169, v[178:179]
	ds_write_b64 v170, v[180:181]
	ds_write_b64 v171, v[182:183]
	v_cvt_pk_bf16_f32 v184, v44, v45
	v_cvt_pk_bf16_f32 v185, v46, v47
	v_cvt_pk_bf16_f32 v186, v36, v37
	v_cvt_pk_bf16_f32 v187, v38, v39
	v_cvt_pk_bf16_f32 v188, v40, v41
	v_cvt_pk_bf16_f32 v189, v42, v43
	v_cvt_pk_bf16_f32 v190, v32, v33
	v_cvt_pk_bf16_f32 v191, v34, v35
	ds_write_b64 v170, v[184:185] offset:8192
	ds_write_b64 v171, v[186:187] offset:8192
	ds_write_b64 v168, v[188:189] offset:8192
	ds_write_b64 v169, v[190:191] offset:8192
	v_cvt_pk_bf16_f32 v176, v28, v29
	v_cvt_pk_bf16_f32 v177, v30, v31
	v_cvt_pk_bf16_f32 v178, v20, v21
	v_cvt_pk_bf16_f32 v179, v22, v23
	v_cvt_pk_bf16_f32 v180, v24, v25
	v_cvt_pk_bf16_f32 v181, v26, v27
	v_cvt_pk_bf16_f32 v182, v16, v17
	v_cvt_pk_bf16_f32 v183, v18, v19
	ds_write_b64 v168, v[176:177] offset:16384
	ds_write_b64 v169, v[178:179] offset:16384
	ds_write_b64 v170, v[180:181] offset:16384
	ds_write_b64 v171, v[182:183] offset:16384
	v_cvt_pk_bf16_f32 v184, v12, v13
	v_cvt_pk_bf16_f32 v185, v14, v15
	v_cvt_pk_bf16_f32 v186, v8, v9
	v_cvt_pk_bf16_f32 v187, v10, v11
	v_cvt_pk_bf16_f32 v188, v4, v5
	v_cvt_pk_bf16_f32 v189, v6, v7
	v_cvt_pk_bf16_f32 v190, v0, v1
	v_cvt_pk_bf16_f32 v191, v2, v3
	ds_write_b64 v170, v[184:185] offset:24576
	ds_write_b64 v171, v[186:187] offset:24576
	ds_write_b64 v168, v[188:189] offset:24576
	ds_write_b64 v169, v[190:191] offset:24576
	s_waitcnt lgkmcnt(0)
	s_barrier
; __device__ __forceinline__ bf16_t f2bf(float f) { return (bf16_t)(pack2(f, 0.f) & 0xffffu); }
; __device__ __forceinline__ float siluf_(float x) { return x * __builtin_amdgcn_rcpf(1.f + __expf(-x)); }
; template <int EPI>
; __device__ __forceinline__ void gemm_tile8p(const bf16_t* __restrict__ Ag, const bf16_t* __restrict__ Bg, int K, int nt, int brow, int bcol,
;                                             char* smem, void* outp, int ldo, int nvalid, int rowoff, int rowlim) {
;     ...
; #pragma unroll
;   for (int ai = 0; ai < 2; ++ai)
; #pragma unroll
;     for (int m = 0; m < 4; ++m)
; #pragma unroll
;       for (int j = 0; j < 4; ++j) {
;         const int rl = ai * HALF + wr * 64 + m * 16 + fq * 4 + j;
;         const size_t orow = (size_t)(rowoff + rl) * ldo;
;         if (EPI == EPI_GLU) {
; #pragma unroll
;           for (int n = 0; n < 2; ++n) {
;             const int col = (bcol >> 8) * 128 + wc * 32 + n * 16 + fr;
;             const float g = acc[ai][0][m][n][j], u = acc[ai][1][m][n][j];
;             if (rl < rowlim) ((bf16_t*)outp)[orow + col] = f2bf(siluf_(g) * u);
;           }
;         } else {
; #pragma unroll
;           for (int bj = 0; bj < 2; ++bj)
; #pragma unroll
;             for (int n = 0; n < 2; ++n) {
;               const int col = bcol + bj * HALF + wc * 32 + n * 16 + fr;
;               const float v = acc[ai][bj][m][n][j];
;               if (EPI == EPI_BF16) { if (rl < rowlim && col < nvalid) ((bf16_t*)outp)[orow + col] = f2bf(v); }
;               else { if (rl < rowlim) ((float*)outp)[orow + col] = v; }
;             }
;         }
;         __builtin_amdgcn_sched_barrier(0);
;       }
	v_lshrrev_b32_e32 v160, 6, v136
	v_lshl_or_b32 v160, v160, 2, v133
	v_lshlrev_b32_e32 v160, 5, v160
	v_or_b32_e32 v160, v160, v161
	v_and_b32_e32 v162, 1, v135
	v_lshl_or_b32 v162, v162, 4, v134
	v_xor_b32_e32 v163, v162, v161
	v_lshlrev_b32_e32 v164, 9, v160
	v_lshl_add_u32 v165, v162, 3, s38
	s_movk_i32 s0, 0xd08
	v_cmp_gt_i32_e64 s[40:41], s0, v165
	v_add_u32_e32 v166, s48, v160
	v_mov_b32_e32 v167, 0
	v_mov_b32_e32 v168, v165
	v_mov_b32_e32 v169, 0
	v_lshl_add_u64 v[168:169], v[168:169], 1, s[68:69]
	v_mad_u64_u32 v[168:169], vcc, v166, s72, v[168:169]
	s_mov_b32 s12, 0x3420
	s_mov_b32 s13, 0
	v_xor_b32_e32 v170, 0, v163
	v_lshl_add_u32 v170, v170, 4, v164
	ds_read_b128 v[176:179], v170 offset:0
	v_xor_b32_e32 v170, 2, v163
	v_lshl_add_u32 v170, v170, 4, v164
	ds_read_b128 v[180:183], v170 offset:1024
	v_xor_b32_e32 v170, 4, v163
	v_lshl_add_u32 v170, v170, 4, v164
	ds_read_b128 v[184:187], v170 offset:2048
	v_xor_b32_e32 v170, 6, v163
	v_lshl_add_u32 v170, v170, 4, v164
	ds_read_b128 v[188:191], v170 offset:3072
	v_add_u32_e32 v171, 0, v160
	v_cmp_gt_i32_e64 s[2:3], s4, v171
	s_waitcnt lgkmcnt(3)
	s_and_b64 exec, s[2:3], s[40:41]
	global_store_dwordx4 v[168:169], v[176:179], off sc1
	s_mov_b64 exec, -1
	v_lshl_add_u64 v[168:169], v[168:169], 0, s[12:13]
	v_add_u32_e32 v171, 2, v160
	v_cmp_gt_i32_e64 s[2:3], s4, v171
	s_waitcnt lgkmcnt(2)
	s_and_b64 exec, s[2:3], s[40:41]
	global_store_dwordx4 v[168:169], v[180:183], off sc1
	s_mov_b64 exec, -1
	v_lshl_add_u64 v[168:169], v[168:169], 0, s[12:13]
	v_add_u32_e32 v171, 4, v160
	v_cmp_gt_i32_e64 s[2:3], s4, v171
	s_waitcnt lgkmcnt(1)
	s_and_b64 exec, s[2:3], s[40:41]
	global_store_dwordx4 v[168:169], v[184:187], off sc1
	s_mov_b64 exec, -1
	v_lshl_add_u64 v[168:169], v[168:169], 0, s[12:13]
	v_add_u32_e32 v171, 6, v160
	v_cmp_gt_i32_e64 s[2:3], s4, v171
	s_waitcnt lgkmcnt(0)
	s_and_b64 exec, s[2:3], s[40:41]
	global_store_dwordx4 v[168:169], v[188:191], off sc1
	s_mov_b64 exec, -1
	v_lshl_add_u64 v[168:169], v[168:169], 0, s[12:13]
	v_xor_b32_e32 v170, 8, v163
	v_lshl_add_u32 v170, v170, 4, v164
	ds_read_b128 v[176:179], v170 offset:4096
	v_xor_b32_e32 v170, 10, v163
	v_lshl_add_u32 v170, v170, 4, v164
	ds_read_b128 v[180:183], v170 offset:5120
	v_xor_b32_e32 v170, 12, v163
	v_lshl_add_u32 v170, v170, 4, v164
	ds_read_b128 v[184:187], v170 offset:6144
	v_xor_b32_e32 v170, 14, v163
	v_lshl_add_u32 v170, v170, 4, v164
	ds_read_b128 v[188:191], v170 offset:7168
	v_add_u32_e32 v171, 8, v160
	v_cmp_gt_i32_e64 s[2:3], s4, v171
	s_waitcnt lgkmcnt(3)
	s_and_b64 exec, s[2:3], s[40:41]
	global_store_dwordx4 v[168:169], v[176:179], off sc1
	s_mov_b64 exec, -1
	v_lshl_add_u64 v[168:169], v[168:169], 0, s[12:13]
	v_add_u32_e32 v171, 10, v160
	v_cmp_gt_i32_e64 s[2:3], s4, v171
	s_waitcnt lgkmcnt(2)
	s_and_b64 exec, s[2:3], s[40:41]
	global_store_dwordx4 v[168:169], v[180:183], off sc1
	s_mov_b64 exec, -1
	v_lshl_add_u64 v[168:169], v[168:169], 0, s[12:13]
	v_add_u32_e32 v171, 12, v160
	v_cmp_gt_i32_e64 s[2:3], s4, v171
	s_waitcnt lgkmcnt(1)
	s_and_b64 exec, s[2:3], s[40:41]
	global_store_dwordx4 v[168:169], v[184:187], off sc1
	s_mov_b64 exec, -1
	v_lshl_add_u64 v[168:169], v[168:169], 0, s[12:13]
	v_add_u32_e32 v171, 14, v160
	v_cmp_gt_i32_e64 s[2:3], s4, v171
	s_waitcnt lgkmcnt(0)
	s_and_b64 exec, s[2:3], s[40:41]
	global_store_dwordx4 v[168:169], v[188:191], off sc1
	s_mov_b64 exec, -1
	v_lshl_add_u64 v[168:169], v[168:169], 0, s[12:13]
	v_xor_b32_e32 v170, 16, v163
	v_lshl_add_u32 v170, v170, 4, v164
	ds_read_b128 v[176:179], v170 offset:8192
	v_xor_b32_e32 v170, 18, v163
	v_lshl_add_u32 v170, v170, 4, v164
	ds_read_b128 v[180:183], v170 offset:9216
	v_xor_b32_e32 v170, 20, v163
	v_lshl_add_u32 v170, v170, 4, v164
	ds_read_b128 v[184:187], v170 offset:10240
	v_xor_b32_e32 v170, 22, v163
	v_lshl_add_u32 v170, v170, 4, v164
	ds_read_b128 v[188:191], v170 offset:11264
	v_add_u32_e32 v171, 16, v160
	v_cmp_gt_i32_e64 s[2:3], s4, v171
	s_waitcnt lgkmcnt(3)
	s_and_b64 exec, s[2:3], s[40:41]
	global_store_dwordx4 v[168:169], v[176:179], off sc1
	s_mov_b64 exec, -1
	v_lshl_add_u64 v[168:169], v[168:169], 0, s[12:13]
	v_add_u32_e32 v171, 18, v160
	v_cmp_gt_i32_e64 s[2:3], s4, v171
	s_waitcnt lgkmcnt(2)
	s_and_b64 exec, s[2:3], s[40:41]
	global_store_dwordx4 v[168:169], v[180:183], off sc1
	s_mov_b64 exec, -1
	v_lshl_add_u64 v[168:169], v[168:169], 0, s[12:13]
	v_add_u32_e32 v171, 20, v160
	v_cmp_gt_i32_e64 s[2:3], s4, v171
	s_waitcnt lgkmcnt(1)
	s_and_b64 exec, s[2:3], s[40:41]
	global_store_dwordx4 v[168:169], v[184:187], off sc1
	s_mov_b64 exec, -1
	v_lshl_add_u64 v[168:169], v[168:169], 0, s[12:13]
	v_add_u32_e32 v171, 22, v160
	v_cmp_gt_i32_e64 s[2:3], s4, v171
	s_waitcnt lgkmcnt(0)
	s_and_b64 exec, s[2:3], s[40:41]
	global_store_dwordx4 v[168:169], v[188:191], off sc1
	s_mov_b64 exec, -1
	v_lshl_add_u64 v[168:169], v[168:169], 0, s[12:13]
	v_xor_b32_e32 v170, 24, v163
	v_lshl_add_u32 v170, v170, 4, v164
	ds_read_b128 v[176:179], v170 offset:12288
	v_xor_b32_e32 v170, 26, v163
	v_lshl_add_u32 v170, v170, 4, v164
	ds_read_b128 v[180:183], v170 offset:13312
	v_xor_b32_e32 v170, 28, v163
	v_lshl_add_u32 v170, v170, 4, v164
	ds_read_b128 v[184:187], v170 offset:14336
	v_xor_b32_e32 v170, 30, v163
	v_lshl_add_u32 v170, v170, 4, v164
	ds_read_b128 v[188:191], v170 offset:15360
	v_add_u32_e32 v171, 24, v160
	v_cmp_gt_i32_e64 s[2:3], s4, v171
	s_waitcnt lgkmcnt(3)
	s_and_b64 exec, s[2:3], s[40:41]
	global_store_dwordx4 v[168:169], v[176:179], off sc1
	s_mov_b64 exec, -1
	v_lshl_add_u64 v[168:169], v[168:169], 0, s[12:13]
	v_add_u32_e32 v171, 26, v160
	v_cmp_gt_i32_e64 s[2:3], s4, v171
	s_waitcnt lgkmcnt(2)
	s_and_b64 exec, s[2:3], s[40:41]
	global_store_dwordx4 v[168:169], v[180:183], off sc1
	s_mov_b64 exec, -1
	v_lshl_add_u64 v[168:169], v[168:169], 0, s[12:13]
	v_add_u32_e32 v171, 28, v160
	v_cmp_gt_i32_e64 s[2:3], s4, v171
	s_waitcnt lgkmcnt(1)
	s_and_b64 exec, s[2:3], s[40:41]
	global_store_dwordx4 v[168:169], v[184:187], off sc1
	s_mov_b64 exec, -1
	v_lshl_add_u64 v[168:169], v[168:169], 0, s[12:13]
	v_add_u32_e32 v171, 30, v160
	v_cmp_gt_i32_e64 s[2:3], s4, v171
	s_waitcnt lgkmcnt(0)
	s_and_b64 exec, s[2:3], s[40:41]
	global_store_dwordx4 v[168:169], v[188:191], off sc1
	s_mov_b64 exec, -1
	v_lshl_add_u64 v[168:169], v[168:169], 0, s[12:13]
	s_branch .LBB0_1060
